# P2 epilogue: write-through (sc1) stores only for a workgroup's last unit; earlier units plain write-back (one scalar branch per store); with barrier edits
# speedup vs baseline: 1.0015x; 1.0015x over previous
;     __device__ bool next(int i, pg8::Unit& u) const { const int L = i * cph + k; if (L >= nunits) return false; const int nig = 8 * nN, gid = L / nig, w = L % nig; u.pm = 16 * xh + 8 * gid + (w & 7); u.pn = w >> 3; return true; }
; template <class Epi, class Sched, bool ALIGN_EPI = false, bool SP2 = false>
; __device__ __forceinline__ void gemm_phase(PG8_LAS unsigned char* lds, const Gemm g, const Sched& S, const Epi& E, volatile PG8_LAS unsigned* sw = nullptr) {
;     ...
;         const bool has_next = S.next(ui + 1, nxt);
.LBB0_159:
	s_add_i32 s43, s43, 1
	s_mul_i32 s3, s43, s62
	s_add_i32 s3, s3, s97
	s_cmpk_lt_i32 s3, 0x80
	s_cselect_b64 s[28:29], -1, 0
	s_cselect_b32 s98, 0, 1
	s_cmpk_gt_i32 s3, 0x7f
	s_cbranch_scc1 .LBB0_161
	s_ashr_i32 s10, s3, 31
	s_lshr_b32 s10, s10, 26
	s_add_i32 s10, s3, s10
	s_ashr_i32 s11, s10, 6
	s_andn2_b32 s10, s10, 63
	s_sub_i32 s3, s3, s10
	s_lshl_b32 s10, s11, 3
	s_add_i32 s10, s10, s60
	s_and_b32 s11, s3, 7
	s_or_b32 s10, s10, s11
	s_ashr_i32 s12, s3, 3

; __device__ __forceinline__ unsigned cvt_pk(float lo, float hi) { f32x2_t v = {lo, hi}; bf16x2_t b = __builtin_convertvector(v, bf16x2_t); return __builtin_bit_cast(unsigned, b); }
;     __device__ __forceinline__ void operator()(AccRef acc, const pg8::Unit& u, int wr, int wc, int fr, int fq) const {
;         const int row0 = u.pm * 256 + wr * 64 + fr, col0 = u.pn * 256 + wc * 32 + 8 * fq;
; #pragma unroll
;         for (int ai = 0; ai < 2; ++ai)
; #pragma unroll
;             for (int m = 0; m < 4; ++m) { bf16* rowp = O + (size_t)(row0 + ai * 128 + m * 16) * INW + col0;
; #pragma unroll
;                 for (int bj = 0; bj < 2; ++bj) { const f32x4 v0 = acc[ai][bj][m][0], v1 = acc[ai][bj][m][1];
;                     v4u w; w.x = cvt_pk(v0[0], v0[1]); w.y = cvt_pk(v0[2], v0[3]); w.z = cvt_pk(v1[0], v1[1]); w.w = cvt_pk(v1[2], v1[3]);
;                     { v4u* pp_ = (v4u*)(rowp + bj * 128); asm volatile("global_store_dwordx4 %0, %1, off sc1\n\ts_nop 2" :: "v"(pp_), "v"(w) : "memory"); } } }
.LBB0_165:
	v_lshl_add_u32 v142, s46, 8, v1
	v_lshl_or_b32 v150, s2, 8, v145
	v_ashrrev_i32_e32 v143, 31, v142
	v_ashrrev_i32_e32 v151, 31, v150
	v_lshlrev_b64 v[152:153], 12, v[142:143]
	v_lshl_add_u64 v[152:153], s[24:25], 0, v[152:153]
	v_lshlrev_b64 v[154:155], 1, v[150:151]
	v_cvt_pk_bf16_f32 v150, v126, v127
	v_lshl_add_u64 v[156:157], v[152:153], 0, v[154:155]
	v_cvt_pk_bf16_f32 v151, v128, v129
	v_cvt_pk_bf16_f32 v152, v122, v123
	v_cvt_pk_bf16_f32 v153, v124, v125
	s_cselect_b32 s100, 1, 0
	s_cmp_lg_u32 s98, 0
	s_cbranch_scc1 .Lwt_p2_0_a
	global_store_dwordx4 v[156:157], v[150:153], off
	s_branch .Lwt_p2_0_b
.Lwt_p2_0_a:
	global_store_dwordx4 v[156:157], v[150:153], off sc1
.Lwt_p2_0_b:
	s_cmp_lg_u32 s100, 0
	s_nop 2
	v_cvt_pk_bf16_f32 v150, v114, v115
	v_cvt_pk_bf16_f32 v151, v116, v117
	v_cvt_pk_bf16_f32 v152, v106, v107
	v_cvt_pk_bf16_f32 v153, v108, v109
	v_lshl_add_u64 v[158:159], v[156:157], 0, s[8:9]
	s_cselect_b32 s100, 1, 0
	s_cmp_lg_u32 s98, 0
	s_cbranch_scc1 .Lwt_p2_1_a
	global_store_dwordx4 v[158:159], v[150:153], off
	s_branch .Lwt_p2_1_b
.Lwt_p2_1_a:
	global_store_dwordx4 v[158:159], v[150:153], off sc1
.Lwt_p2_1_b:
	s_cmp_lg_u32 s100, 0
	s_nop 2
	v_or_b32_e32 v150, 16, v142
	v_ashrrev_i32_e32 v151, 31, v150
	v_lshlrev_b64 v[150:151], 12, v[150:151]
	v_lshl_add_u64 v[150:151], s[24:25], 0, v[150:151]
	v_lshl_add_u64 v[158:159], v[150:151], 0, v[154:155]
	v_cvt_pk_bf16_f32 v150, v118, v119
	v_cvt_pk_bf16_f32 v151, v120, v121
	v_cvt_pk_bf16_f32 v152, v110, v111
	v_cvt_pk_bf16_f32 v153, v112, v113
	s_cselect_b32 s100, 1, 0
	s_cmp_lg_u32 s98, 0
	s_cbranch_scc1 .Lwt_p2_2_a
	global_store_dwordx4 v[158:159], v[150:153], off
	s_branch .Lwt_p2_2_b

; __device__ __forceinline__ unsigned cvt_pk(float lo, float hi) { f32x2_t v = {lo, hi}; bf16x2_t b = __builtin_convertvector(v, bf16x2_t); return __builtin_bit_cast(unsigned, b); }
;     __device__ __forceinline__ void operator()(AccRef acc, const pg8::Unit& u, int wr, int wc, int fr, int fq) const {
;     ...
;             for (int m = 0; m < 4; ++m) { bf16* rowp = O + (size_t)(row0 + ai * 128 + m * 16) * INW + col0;
; #pragma unroll
;                 for (int bj = 0; bj < 2; ++bj) { const f32x4 v0 = acc[ai][bj][m][0], v1 = acc[ai][bj][m][1];
;                     v4u w; w.x = cvt_pk(v0[0], v0[1]); w.y = cvt_pk(v0[2], v0[3]); w.z = cvt_pk(v1[0], v1[1]); w.w = cvt_pk(v1[2], v1[3]);
;                     { v4u* pp_ = (v4u*)(rowp + bj * 128); asm volatile("global_store_dwordx4 %0, %1, off sc1\n\ts_nop 2" :: "v"(pp_), "v"(w) : "memory"); } } }
.Lwt_p2_2_b:
	s_cmp_lg_u32 s100, 0
	s_nop 2
	v_cvt_pk_bf16_f32 v150, v98, v99
	v_cvt_pk_bf16_f32 v151, v100, v101
	v_cvt_pk_bf16_f32 v152, v90, v91
	v_cvt_pk_bf16_f32 v153, v92, v93
	v_lshl_add_u64 v[158:159], v[158:159], 0, s[8:9]
	s_cselect_b32 s100, 1, 0
	s_cmp_lg_u32 s98, 0
	s_cbranch_scc1 .Lwt_p2_3_a
	global_store_dwordx4 v[158:159], v[150:153], off
	s_branch .Lwt_p2_3_b

; __device__ __forceinline__ unsigned cvt_pk(float lo, float hi) { f32x2_t v = {lo, hi}; bf16x2_t b = __builtin_convertvector(v, bf16x2_t); return __builtin_bit_cast(unsigned, b); }
;     __device__ __forceinline__ void operator()(AccRef acc, const pg8::Unit& u, int wr, int wc, int fr, int fq) const {
;     ...
;             for (int m = 0; m < 4; ++m) { bf16* rowp = O + (size_t)(row0 + ai * 128 + m * 16) * INW + col0;
; #pragma unroll
;                 for (int bj = 0; bj < 2; ++bj) { const f32x4 v0 = acc[ai][bj][m][0], v1 = acc[ai][bj][m][1];
;                     v4u w; w.x = cvt_pk(v0[0], v0[1]); w.y = cvt_pk(v0[2], v0[3]); w.z = cvt_pk(v1[0], v1[1]); w.w = cvt_pk(v1[2], v1[3]);
;                     { v4u* pp_ = (v4u*)(rowp + bj * 128); asm volatile("global_store_dwordx4 %0, %1, off sc1\n\ts_nop 2" :: "v"(pp_), "v"(w) : "memory"); } } }
.Lwt_p2_3_b:
	s_cmp_lg_u32 s100, 0
	s_nop 2
	v_or_b32_e32 v150, 32, v142
	v_ashrrev_i32_e32 v151, 31, v150
	v_lshlrev_b64 v[150:151], 12, v[150:151]
	v_lshl_add_u64 v[150:151], s[24:25], 0, v[150:151]
	v_lshl_add_u64 v[158:159], v[150:151], 0, v[154:155]
	v_cvt_pk_bf16_f32 v150, v102, v103
	v_cvt_pk_bf16_f32 v151, v104, v105
	v_cvt_pk_bf16_f32 v152, v94, v95
	v_cvt_pk_bf16_f32 v153, v96, v97
	s_cselect_b32 s100, 1, 0
	s_cmp_lg_u32 s98, 0
	s_cbranch_scc1 .Lwt_p2_4_a
	global_store_dwordx4 v[158:159], v[150:153], off
	s_branch .Lwt_p2_4_b

; __device__ __forceinline__ unsigned cvt_pk(float lo, float hi) { f32x2_t v = {lo, hi}; bf16x2_t b = __builtin_convertvector(v, bf16x2_t); return __builtin_bit_cast(unsigned, b); }
;     __device__ __forceinline__ void operator()(AccRef acc, const pg8::Unit& u, int wr, int wc, int fr, int fq) const {
;     ...
;             for (int m = 0; m < 4; ++m) { bf16* rowp = O + (size_t)(row0 + ai * 128 + m * 16) * INW + col0;
; #pragma unroll
;                 for (int bj = 0; bj < 2; ++bj) { const f32x4 v0 = acc[ai][bj][m][0], v1 = acc[ai][bj][m][1];
;                     v4u w; w.x = cvt_pk(v0[0], v0[1]); w.y = cvt_pk(v0[2], v0[3]); w.z = cvt_pk(v1[0], v1[1]); w.w = cvt_pk(v1[2], v1[3]);
;                     { v4u* pp_ = (v4u*)(rowp + bj * 128); asm volatile("global_store_dwordx4 %0, %1, off sc1\n\ts_nop 2" :: "v"(pp_), "v"(w) : "memory"); } } }
.Lwt_p2_4_b:
	s_cmp_lg_u32 s100, 0
	s_nop 2
	v_cvt_pk_bf16_f32 v150, v82, v83
	v_cvt_pk_bf16_f32 v151, v84, v85
	v_cvt_pk_bf16_f32 v152, v74, v75
	v_cvt_pk_bf16_f32 v153, v76, v77
	v_lshl_add_u64 v[158:159], v[158:159], 0, s[8:9]
	s_cselect_b32 s100, 1, 0
	s_cmp_lg_u32 s98, 0
	s_cbranch_scc1 .Lwt_p2_5_a
	global_store_dwordx4 v[158:159], v[150:153], off
	s_branch .Lwt_p2_5_b

; __device__ __forceinline__ unsigned cvt_pk(float lo, float hi) { f32x2_t v = {lo, hi}; bf16x2_t b = __builtin_convertvector(v, bf16x2_t); return __builtin_bit_cast(unsigned, b); }
;     __device__ __forceinline__ void operator()(AccRef acc, const pg8::Unit& u, int wr, int wc, int fr, int fq) const {
;     ...
;             for (int m = 0; m < 4; ++m) { bf16* rowp = O + (size_t)(row0 + ai * 128 + m * 16) * INW + col0;
; #pragma unroll
;                 for (int bj = 0; bj < 2; ++bj) { const f32x4 v0 = acc[ai][bj][m][0], v1 = acc[ai][bj][m][1];
;                     v4u w; w.x = cvt_pk(v0[0], v0[1]); w.y = cvt_pk(v0[2], v0[3]); w.z = cvt_pk(v1[0], v1[1]); w.w = cvt_pk(v1[2], v1[3]);
;                     { v4u* pp_ = (v4u*)(rowp + bj * 128); asm volatile("global_store_dwordx4 %0, %1, off sc1\n\ts_nop 2" :: "v"(pp_), "v"(w) : "memory"); } } }
.Lwt_p2_5_b:
	s_cmp_lg_u32 s100, 0
	s_nop 2
	v_or_b32_e32 v150, 48, v142
	v_ashrrev_i32_e32 v151, 31, v150
	v_lshlrev_b64 v[150:151], 12, v[150:151]
	v_lshl_add_u64 v[150:151], s[24:25], 0, v[150:151]
	v_lshl_add_u64 v[154:155], v[150:151], 0, v[154:155]
	v_cvt_pk_bf16_f32 v150, v86, v87
	v_cvt_pk_bf16_f32 v151, v88, v89
	v_cvt_pk_bf16_f32 v152, v78, v79
	v_cvt_pk_bf16_f32 v153, v80, v81
	s_cselect_b32 s100, 1, 0
	s_cmp_lg_u32 s98, 0
	s_cbranch_scc1 .Lwt_p2_6_a
	global_store_dwordx4 v[154:155], v[150:153], off
	s_branch .Lwt_p2_6_b
.Lwt_p2_6_a:
	global_store_dwordx4 v[154:155], v[150:153], off sc1
.Lwt_p2_6_b:
	s_cmp_lg_u32 s100, 0
	s_nop 2
	v_cvt_pk_bf16_f32 v150, v70, v71
	v_cvt_pk_bf16_f32 v151, v72, v73
	v_cvt_pk_bf16_f32 v152, v66, v67
	v_cvt_pk_bf16_f32 v153, v68, v69
	v_lshl_add_u64 v[154:155], v[154:155], 0, s[8:9]
	s_cselect_b32 s100, 1, 0
	s_cmp_lg_u32 s98, 0
	s_cbranch_scc1 .Lwt_p2_7_a
	global_store_dwordx4 v[154:155], v[150:153], off
	s_branch .Lwt_p2_7_b

; __device__ __forceinline__ unsigned cvt_pk(float lo, float hi) { f32x2_t v = {lo, hi}; bf16x2_t b = __builtin_convertvector(v, bf16x2_t); return __builtin_bit_cast(unsigned, b); }
;     __device__ __forceinline__ void operator()(AccRef acc, const pg8::Unit& u, int wr, int wc, int fr, int fq) const {
;     ...
;             for (int m = 0; m < 4; ++m) { bf16* rowp = O + (size_t)(row0 + ai * 128 + m * 16) * INW + col0;
; #pragma unroll
;                 for (int bj = 0; bj < 2; ++bj) { const f32x4 v0 = acc[ai][bj][m][0], v1 = acc[ai][bj][m][1];
;                     v4u w; w.x = cvt_pk(v0[0], v0[1]); w.y = cvt_pk(v0[2], v0[3]); w.z = cvt_pk(v1[0], v1[1]); w.w = cvt_pk(v1[2], v1[3]);
;                     { v4u* pp_ = (v4u*)(rowp + bj * 128); asm volatile("global_store_dwordx4 %0, %1, off sc1\n\ts_nop 2" :: "v"(pp_), "v"(w) : "memory"); } } }
.Lwt_p2_7_b:
	s_cmp_lg_u32 s100, 0
	s_nop 2
	s_mov_b64 s[46:47], 0x80000
	v_lshl_add_u64 v[154:155], v[156:157], 0, s[46:47]
	v_cvt_pk_bf16_f32 v150, v62, v63
	v_cvt_pk_bf16_f32 v151, v64, v65
	v_cvt_pk_bf16_f32 v152, v58, v59
	v_cvt_pk_bf16_f32 v153, v60, v61
	s_cselect_b32 s100, 1, 0
	s_cmp_lg_u32 s98, 0
	s_cbranch_scc1 .Lwt_p2_8_a
	global_store_dwordx4 v[154:155], v[150:153], off
	s_branch .Lwt_p2_8_b

; __device__ __forceinline__ unsigned cvt_pk(float lo, float hi) { f32x2_t v = {lo, hi}; bf16x2_t b = __builtin_convertvector(v, bf16x2_t); return __builtin_bit_cast(unsigned, b); }
;     __device__ __forceinline__ void operator()(AccRef acc, const pg8::Unit& u, int wr, int wc, int fr, int fq) const {
;     ...
;             for (int m = 0; m < 4; ++m) { bf16* rowp = O + (size_t)(row0 + ai * 128 + m * 16) * INW + col0;
; #pragma unroll
;                 for (int bj = 0; bj < 2; ++bj) { const f32x4 v0 = acc[ai][bj][m][0], v1 = acc[ai][bj][m][1];
;                     v4u w; w.x = cvt_pk(v0[0], v0[1]); w.y = cvt_pk(v0[2], v0[3]); w.z = cvt_pk(v1[0], v1[1]); w.w = cvt_pk(v1[2], v1[3]);
;                     { v4u* pp_ = (v4u*)(rowp + bj * 128); asm volatile("global_store_dwordx4 %0, %1, off sc1\n\ts_nop 2" :: "v"(pp_), "v"(w) : "memory"); } } }
.Lwt_p2_8_b:
	s_cmp_lg_u32 s100, 0
	s_nop 2
	s_mov_b64 s[46:47], 0x80100
	v_cvt_pk_bf16_f32 v150, v50, v51
	v_cvt_pk_bf16_f32 v151, v52, v53
	v_cvt_pk_bf16_f32 v152, v42, v43
	v_cvt_pk_bf16_f32 v153, v44, v45
	v_lshl_add_u64 v[154:155], v[156:157], 0, s[46:47]
	s_cselect_b32 s100, 1, 0
	s_cmp_lg_u32 s98, 0
	s_cbranch_scc1 .Lwt_p2_9_a
	global_store_dwordx4 v[154:155], v[150:153], off
	s_branch .Lwt_p2_9_b

; __device__ __forceinline__ unsigned cvt_pk(float lo, float hi) { f32x2_t v = {lo, hi}; bf16x2_t b = __builtin_convertvector(v, bf16x2_t); return __builtin_bit_cast(unsigned, b); }
;     __device__ __forceinline__ void operator()(AccRef acc, const pg8::Unit& u, int wr, int wc, int fr, int fq) const {
;     ...
;             for (int m = 0; m < 4; ++m) { bf16* rowp = O + (size_t)(row0 + ai * 128 + m * 16) * INW + col0;
; #pragma unroll
;                 for (int bj = 0; bj < 2; ++bj) { const f32x4 v0 = acc[ai][bj][m][0], v1 = acc[ai][bj][m][1];
;                     v4u w; w.x = cvt_pk(v0[0], v0[1]); w.y = cvt_pk(v0[2], v0[3]); w.z = cvt_pk(v1[0], v1[1]); w.w = cvt_pk(v1[2], v1[3]);
;                     { v4u* pp_ = (v4u*)(rowp + bj * 128); asm volatile("global_store_dwordx4 %0, %1, off sc1\n\ts_nop 2" :: "v"(pp_), "v"(w) : "memory"); } } }
.Lwt_p2_9_b:
	s_cmp_lg_u32 s100, 0
	s_nop 2
	s_mov_b64 s[46:47], 0x90000
	v_lshl_add_u64 v[154:155], v[156:157], 0, s[46:47]
	v_cvt_pk_bf16_f32 v150, v54, v55
	v_cvt_pk_bf16_f32 v151, v56, v57
	v_cvt_pk_bf16_f32 v152, v46, v47
	v_cvt_pk_bf16_f32 v153, v48, v49
	s_cselect_b32 s100, 1, 0
	s_cmp_lg_u32 s98, 0
	s_cbranch_scc1 .Lwt_p2_10_a
	global_store_dwordx4 v[154:155], v[150:153], off
	s_branch .Lwt_p2_10_b

; __device__ __forceinline__ unsigned cvt_pk(float lo, float hi) { f32x2_t v = {lo, hi}; bf16x2_t b = __builtin_convertvector(v, bf16x2_t); return __builtin_bit_cast(unsigned, b); }
;     __device__ __forceinline__ void operator()(AccRef acc, const pg8::Unit& u, int wr, int wc, int fr, int fq) const {
;     ...
;             for (int m = 0; m < 4; ++m) { bf16* rowp = O + (size_t)(row0 + ai * 128 + m * 16) * INW + col0;
; #pragma unroll
;                 for (int bj = 0; bj < 2; ++bj) { const f32x4 v0 = acc[ai][bj][m][0], v1 = acc[ai][bj][m][1];
;                     v4u w; w.x = cvt_pk(v0[0], v0[1]); w.y = cvt_pk(v0[2], v0[3]); w.z = cvt_pk(v1[0], v1[1]); w.w = cvt_pk(v1[2], v1[3]);
;                     { v4u* pp_ = (v4u*)(rowp + bj * 128); asm volatile("global_store_dwordx4 %0, %1, off sc1\n\ts_nop 2" :: "v"(pp_), "v"(w) : "memory"); } } }
.Lwt_p2_10_b:
	s_cmp_lg_u32 s100, 0
	s_nop 2
	s_mov_b64 s[46:47], 0x90100
	v_cvt_pk_bf16_f32 v150, v34, v35
	v_cvt_pk_bf16_f32 v151, v36, v37
	v_cvt_pk_bf16_f32 v152, v26, v27
	v_cvt_pk_bf16_f32 v153, v28, v29
	v_lshl_add_u64 v[154:155], v[156:157], 0, s[46:47]
	s_cselect_b32 s100, 1, 0
	s_cmp_lg_u32 s98, 0
	s_cbranch_scc1 .Lwt_p2_11_a
	global_store_dwordx4 v[154:155], v[150:153], off
	s_branch .Lwt_p2_11_b

; __device__ __forceinline__ unsigned cvt_pk(float lo, float hi) { f32x2_t v = {lo, hi}; bf16x2_t b = __builtin_convertvector(v, bf16x2_t); return __builtin_bit_cast(unsigned, b); }
;     __device__ __forceinline__ void operator()(AccRef acc, const pg8::Unit& u, int wr, int wc, int fr, int fq) const {
;     ...
;             for (int m = 0; m < 4; ++m) { bf16* rowp = O + (size_t)(row0 + ai * 128 + m * 16) * INW + col0;
; #pragma unroll
;                 for (int bj = 0; bj < 2; ++bj) { const f32x4 v0 = acc[ai][bj][m][0], v1 = acc[ai][bj][m][1];
;                     v4u w; w.x = cvt_pk(v0[0], v0[1]); w.y = cvt_pk(v0[2], v0[3]); w.z = cvt_pk(v1[0], v1[1]); w.w = cvt_pk(v1[2], v1[3]);
;                     { v4u* pp_ = (v4u*)(rowp + bj * 128); asm volatile("global_store_dwordx4 %0, %1, off sc1\n\ts_nop 2" :: "v"(pp_), "v"(w) : "memory"); } } }
.Lwt_p2_11_b:
	s_cmp_lg_u32 s100, 0
	s_nop 2
	s_mov_b64 s[46:47], 0xa0000
	v_lshl_add_u64 v[154:155], v[156:157], 0, s[46:47]
	v_cvt_pk_bf16_f32 v150, v38, v39
	v_cvt_pk_bf16_f32 v151, v40, v41
	v_cvt_pk_bf16_f32 v152, v30, v31
	v_cvt_pk_bf16_f32 v153, v32, v33
	s_cselect_b32 s100, 1, 0
	s_cmp_lg_u32 s98, 0
	s_cbranch_scc1 .Lwt_p2_12_a
	global_store_dwordx4 v[154:155], v[150:153], off
	s_branch .Lwt_p2_12_b

; __device__ __forceinline__ unsigned cvt_pk(float lo, float hi) { f32x2_t v = {lo, hi}; bf16x2_t b = __builtin_convertvector(v, bf16x2_t); return __builtin_bit_cast(unsigned, b); }
;     __device__ __forceinline__ void operator()(AccRef acc, const pg8::Unit& u, int wr, int wc, int fr, int fq) const {
;     ...
;             for (int m = 0; m < 4; ++m) { bf16* rowp = O + (size_t)(row0 + ai * 128 + m * 16) * INW + col0;
; #pragma unroll
;                 for (int bj = 0; bj < 2; ++bj) { const f32x4 v0 = acc[ai][bj][m][0], v1 = acc[ai][bj][m][1];
;                     v4u w; w.x = cvt_pk(v0[0], v0[1]); w.y = cvt_pk(v0[2], v0[3]); w.z = cvt_pk(v1[0], v1[1]); w.w = cvt_pk(v1[2], v1[3]);
;                     { v4u* pp_ = (v4u*)(rowp + bj * 128); asm volatile("global_store_dwordx4 %0, %1, off sc1\n\ts_nop 2" :: "v"(pp_), "v"(w) : "memory"); } } }
.Lwt_p2_12_b:
	s_cmp_lg_u32 s100, 0
	s_nop 2
	s_mov_b64 s[46:47], 0xa0100
	v_cvt_pk_bf16_f32 v150, v18, v19
	v_cvt_pk_bf16_f32 v151, v20, v21
	v_cvt_pk_bf16_f32 v152, v10, v11
	v_cvt_pk_bf16_f32 v153, v12, v13
	v_lshl_add_u64 v[154:155], v[156:157], 0, s[46:47]
	s_cselect_b32 s100, 1, 0
	s_cmp_lg_u32 s98, 0
	s_cbranch_scc1 .Lwt_p2_13_a
	global_store_dwordx4 v[154:155], v[150:153], off
	s_branch .Lwt_p2_13_b

; __device__ __forceinline__ unsigned cvt_pk(float lo, float hi) { f32x2_t v = {lo, hi}; bf16x2_t b = __builtin_convertvector(v, bf16x2_t); return __builtin_bit_cast(unsigned, b); }
;     __device__ __forceinline__ void operator()(AccRef acc, const pg8::Unit& u, int wr, int wc, int fr, int fq) const {
;     ...
;             for (int m = 0; m < 4; ++m) { bf16* rowp = O + (size_t)(row0 + ai * 128 + m * 16) * INW + col0;
; #pragma unroll
;                 for (int bj = 0; bj < 2; ++bj) { const f32x4 v0 = acc[ai][bj][m][0], v1 = acc[ai][bj][m][1];
;                     v4u w; w.x = cvt_pk(v0[0], v0[1]); w.y = cvt_pk(v0[2], v0[3]); w.z = cvt_pk(v1[0], v1[1]); w.w = cvt_pk(v1[2], v1[3]);
;                     { v4u* pp_ = (v4u*)(rowp + bj * 128); asm volatile("global_store_dwordx4 %0, %1, off sc1\n\ts_nop 2" :: "v"(pp_), "v"(w) : "memory"); } } }
.Lwt_p2_13_b:
	s_cmp_lg_u32 s100, 0
	s_nop 2
	s_mov_b64 s[46:47], 0xb0000
	v_lshl_add_u64 v[154:155], v[156:157], 0, s[46:47]
	v_cvt_pk_bf16_f32 v150, v22, v23
	v_cvt_pk_bf16_f32 v151, v24, v25
	v_cvt_pk_bf16_f32 v152, v14, v15
	v_cvt_pk_bf16_f32 v153, v16, v17
	s_cselect_b32 s100, 1, 0
	s_cmp_lg_u32 s98, 0
	s_cbranch_scc1 .Lwt_p2_14_a
	global_store_dwordx4 v[154:155], v[150:153], off
	s_branch .Lwt_p2_14_b

; __device__ __forceinline__ unsigned cvt_pk(float lo, float hi) { f32x2_t v = {lo, hi}; bf16x2_t b = __builtin_convertvector(v, bf16x2_t); return __builtin_bit_cast(unsigned, b); }
;     __device__ __forceinline__ void operator()(AccRef acc, const pg8::Unit& u, int wr, int wc, int fr, int fq) const {
;     ...
;             for (int m = 0; m < 4; ++m) { bf16* rowp = O + (size_t)(row0 + ai * 128 + m * 16) * INW + col0;
; #pragma unroll
;                 for (int bj = 0; bj < 2; ++bj) { const f32x4 v0 = acc[ai][bj][m][0], v1 = acc[ai][bj][m][1];
;                     v4u w; w.x = cvt_pk(v0[0], v0[1]); w.y = cvt_pk(v0[2], v0[3]); w.z = cvt_pk(v1[0], v1[1]); w.w = cvt_pk(v1[2], v1[3]);
;                     { v4u* pp_ = (v4u*)(rowp + bj * 128); asm volatile("global_store_dwordx4 %0, %1, off sc1\n\ts_nop 2" :: "v"(pp_), "v"(w) : "memory"); } } }
.Lwt_p2_14_b:
	s_cmp_lg_u32 s100, 0
	s_nop 2
	s_mov_b64 s[46:47], 0xb0100
	v_cvt_pk_bf16_f32 v150, v6, v7
	v_cvt_pk_bf16_f32 v151, v8, v9
	v_cvt_pk_bf16_f32 v152, v2, v3
	v_cvt_pk_bf16_f32 v153, v4, v5
	v_lshl_add_u64 v[154:155], v[156:157], 0, s[46:47]
	s_cselect_b32 s100, 1, 0
	s_cmp_lg_u32 s98, 0
	s_cbranch_scc1 .Lwt_p2_15_a
	global_store_dwordx4 v[154:155], v[150:153], off
	s_branch .Lwt_p2_15_b

;     __device__ __forceinline__ void operator()(AccRef acc, const pg8::Unit& u, int wr, int wc, int fr, int fq) const {
;     ...
;         if (u.pn < 4) {
;             float sr[2][4][2];
; #pragma unroll
;             for (int ai = 0; ai < 2; ++ai)
; #pragma unroll
;                 for (int m = 0; m < 4; ++m)
; #pragma unroll
;                     for (int bj = 0; bj < 2; ++bj) { const f32x4 v0 = acc[ai][bj][m][0], v1 = acc[ai][bj][m][1];
;                         sr[ai][m][bj] = red_sum_16_32(((v0[0] * v0[0] + v0[1] * v0[1]) + (v0[2] * v0[2] + v0[3] * v0[3])) + ((v1[0] * v1[0] + v1[1] * v1[1]) + (v1[2] * v1[2] + v1[3] * v1[3]))); }
.Lwt_p2_15_b:
	s_cmp_lg_u32 s100, 0
	s_nop 2
	s_cmp_gt_i32 s2, 3
	s_cbranch_scc1 .LBB0_169
	v_mul_f32_e32 v127, v127, v127
	v_mul_f32_e32 v123, v123, v123
	v_fmac_f32_e32 v127, v126, v126
	v_mul_f32_e32 v126, v129, v129
	v_fmac_f32_e32 v123, v122, v122
	v_mul_f32_e32 v122, v125, v125
	v_fmac_f32_e32 v126, v128, v128
	v_fmac_f32_e32 v122, v124, v124
	v_mul_f32_e32 v107, v107, v107
	v_add_f32_e32 v126, v127, v126
	v_add_f32_e32 v122, v123, v122
	v_mul_f32_e32 v115, v115, v115
	v_fmac_f32_e32 v107, v106, v106
	v_mul_f32_e32 v106, v109, v109
	v_add_f32_e32 v122, v126, v122
	v_fmac_f32_e32 v115, v114, v114
	v_mul_f32_e32 v114, v117, v117
	v_fmac_f32_e32 v106, v108, v108
	v_mul_f32_e32 v108, v119, v119
	v_mul_f32_e32 v109, v121, v121
	v_mov_b32_e32 v123, v122
	v_fmac_f32_e32 v114, v116, v116
	v_fmac_f32_e32 v108, v118, v118
	v_fmac_f32_e32 v109, v120, v120
	s_nop 1
	v_permlane16_swap_b32 v123, v122
	v_add_f32_e32 v114, v115, v114
	v_add_f32_e32 v106, v107, v106
	v_add_f32_e32 v108, v108, v109
	v_mul_f32_e32 v109, v111, v111
	v_add_f32_e32 v122, v123, v122
	v_add_f32_e32 v106, v114, v106
	v_fmac_f32_e32 v109, v110, v110
	v_mul_f32_e32 v110, v113, v113
	v_mov_b32_e32 v123, v122
	v_mov_b32_e32 v107, v106
	v_fmac_f32_e32 v110, v112, v112
	v_mul_f32_e32 v91, v91, v91
	s_nop 1
	v_permlane32_swap_b32 v123, v122
	s_nop 1
	v_permlane16_swap_b32 v107, v106
	v_add_f32_e32 v109, v109, v110
	v_mul_f32_e32 v99, v99, v99
	v_fmac_f32_e32 v91, v90, v90
	v_mul_f32_e32 v90, v93, v93
	v_add_f32_e32 v106, v107, v106
	v_add_f32_e32 v108, v108, v109
	v_fmac_f32_e32 v99, v98, v98
	v_mul_f32_e32 v98, v101, v101
	v_fmac_f32_e32 v90, v92, v92
	v_mul_f32_e32 v92, v103, v103
	v_mul_f32_e32 v93, v105, v105
	v_mov_b32_e32 v107, v106
	v_mov_b32_e32 v109, v108
	v_fmac_f32_e32 v98, v100, v100
	v_fmac_f32_e32 v92, v102, v102
	v_fmac_f32_e32 v93, v104, v104
	s_nop 1
	v_permlane32_swap_b32 v107, v106
	s_nop 1
	v_permlane16_swap_b32 v109, v108
	v_add_f32_e32 v98, v99, v98
	v_add_f32_e32 v90, v91, v90
	v_add_f32_e32 v92, v92, v93
	v_mul_f32_e32 v93, v95, v95
	v_add_f32_e32 v108, v109, v108
	v_add_f32_e32 v90, v98, v90
	v_fmac_f32_e32 v93, v94, v94
	v_mul_f32_e32 v94, v97, v97
	v_mov_b32_e32 v109, v108
	v_mov_b32_e32 v91, v90
	v_fmac_f32_e32 v94, v96, v96
	v_mul_f32_e32 v75, v75, v75
	s_nop 1
	v_permlane32_swap_b32 v109, v108
	s_nop 1
	v_permlane16_swap_b32 v91, v90
	v_add_f32_e32 v93, v93, v94
	v_mul_f32_e32 v83, v83, v83
	v_fmac_f32_e32 v75, v74, v74
	v_mul_f32_e32 v74, v77, v77
	v_add_f32_e32 v90, v91, v90
	v_add_f32_e32 v92, v92, v93
	v_fmac_f32_e32 v83, v82, v82
	v_mul_f32_e32 v82, v85, v85
	v_fmac_f32_e32 v74, v76, v76
	v_mul_f32_e32 v76, v87, v87
	v_mul_f32_e32 v77, v89, v89
	v_mov_b32_e32 v91, v90
	v_mov_b32_e32 v93, v92
	v_fmac_f32_e32 v82, v84, v84
	v_fmac_f32_e32 v76, v86, v86
	v_fmac_f32_e32 v77, v88, v88
	s_nop 1
	v_permlane32_swap_b32 v91, v90
	s_nop 1
	v_permlane16_swap_b32 v93, v92
	v_add_f32_e32 v82, v83, v82
	v_add_f32_e32 v74, v75, v74
	v_add_f32_e32 v76, v76, v77
	v_mul_f32_e32 v77, v79, v79
	v_add_f32_e32 v92, v93, v92
	v_add_f32_e32 v74, v82, v74
	v_fmac_f32_e32 v77, v78, v78
	v_mul_f32_e32 v78, v81, v81
	v_mov_b32_e32 v93, v92
	v_mov_b32_e32 v75, v74
	v_fmac_f32_e32 v78, v80, v80
	s_nop 1
	v_permlane32_swap_b32 v93, v92
	s_nop 1
	v_permlane16_swap_b32 v75, v74
	v_add_f32_e32 v77, v77, v78
	v_mul_f32_e32 v71, v71, v71
	v_mul_f32_e32 v67, v67, v67
	v_add_f32_e32 v74, v75, v74
	v_add_f32_e32 v76, v76, v77
	v_fmac_f32_e32 v71, v70, v70
	v_mul_f32_e32 v70, v73, v73
	v_fmac_f32_e32 v67, v66, v66
	v_mul_f32_e32 v66, v69, v69
	v_mov_b32_e32 v75, v74
	v_mov_b32_e32 v77, v76
	v_fmac_f32_e32 v70, v72, v72
	v_fmac_f32_e32 v66, v68, v68
	s_nop 1
	v_permlane32_swap_b32 v75, v74
	s_nop 1
	v_permlane16_swap_b32 v77, v76
	v_add_f32_e32 v70, v71, v70
	v_add_f32_e32 v66, v67, v66
	v_mul_f32_e32 v63, v63, v63
	v_mul_f32_e32 v59, v59, v59
	v_add_f32_e32 v76, v77, v76
	v_add_f32_e32 v66, v70, v66
	v_fmac_f32_e32 v63, v62, v62
	v_mul_f32_e32 v62, v65, v65
	v_fmac_f32_e32 v59, v58, v58
	v_mul_f32_e32 v58, v61, v61
	v_mov_b32_e32 v77, v76
	v_mov_b32_e32 v67, v66
	v_fmac_f32_e32 v62, v64, v64
	v_fmac_f32_e32 v58, v60, v60
	v_mul_f32_e32 v43, v43, v43
	s_nop 1
	v_permlane32_swap_b32 v77, v76
	s_nop 1
	v_permlane16_swap_b32 v67, v66
	v_add_f32_e32 v62, v63, v62
	v_add_f32_e32 v58, v59, v58
	v_mul_f32_e32 v51, v51, v51
	v_fmac_f32_e32 v43, v42, v42
	v_mul_f32_e32 v42, v45, v45
	v_add_f32_e32 v66, v67, v66
	v_add_f32_e32 v58, v62, v58
	v_fmac_f32_e32 v51, v50, v50
	v_mul_f32_e32 v50, v53, v53
	v_fmac_f32_e32 v42, v44, v44
	v_mul_f32_e32 v44, v55, v55
	v_mul_f32_e32 v45, v57, v57
	v_mov_b32_e32 v67, v66
	v_mov_b32_e32 v59, v58
	v_fmac_f32_e32 v50, v52, v52
	v_fmac_f32_e32 v44, v54, v54
	v_fmac_f32_e32 v45, v56, v56
	s_nop 1
	v_permlane32_swap_b32 v67, v66
	s_nop 1
;     __device__ __forceinline__ void operator()(AccRef acc, const pg8::Unit& u, int wr, int wc, int fr, int fq) const {
;     ...
;                         sr[ai][m][bj] = red_sum_16_32(((v0[0] * v0[0] + v0[1] * v0[1]) + (v0[2] * v0[2] + v0[3] * v0[3])) + ((v1[0] * v1[0] + v1[1] * v1[1]) + (v1[2] * v1[2] + v1[3] * v1[3]))); }
;             if (fq == 0) {
; #pragma unroll
;                 for (int ai = 0; ai < 2; ++ai)
; #pragma unroll
;                     for (int m = 0; m < 4; ++m)
; #pragma unroll
;                         for (int bj = 0; bj < 2; ++bj) atomicAdd(hss + (size_t)(4 * u.pn + 2 * bj + (wc >> 1)) * MT + pm0 * 256 + row0 + ai * 128 + m * 16, sr[ai][m][bj] * asc);
	v_permlane16_swap_b32 v59, v58
	v_add_f32_e32 v50, v51, v50
	v_add_f32_e32 v42, v43, v42
	v_add_f32_e32 v44, v44, v45
	v_mul_f32_e32 v45, v47, v47
	v_add_f32_e32 v58, v59, v58
	v_add_f32_e32 v42, v50, v42
	v_fmac_f32_e32 v45, v46, v46
	v_mul_f32_e32 v46, v49, v49
	v_mov_b32_e32 v59, v58
	v_mov_b32_e32 v43, v42
	v_fmac_f32_e32 v46, v48, v48
	v_mul_f32_e32 v27, v27, v27
	s_nop 1
	v_permlane32_swap_b32 v59, v58
	s_nop 1
	v_permlane16_swap_b32 v43, v42
	v_add_f32_e32 v45, v45, v46
	v_mul_f32_e32 v35, v35, v35
	v_fmac_f32_e32 v27, v26, v26
	v_mul_f32_e32 v26, v29, v29
	v_add_f32_e32 v42, v43, v42
	v_add_f32_e32 v44, v44, v45
	v_fmac_f32_e32 v35, v34, v34
	v_mul_f32_e32 v34, v37, v37
	v_fmac_f32_e32 v26, v28, v28
	v_mul_f32_e32 v28, v39, v39
	v_mul_f32_e32 v29, v41, v41
	v_mov_b32_e32 v43, v42
	v_mov_b32_e32 v45, v44
	v_fmac_f32_e32 v34, v36, v36
	v_fmac_f32_e32 v28, v38, v38
	v_fmac_f32_e32 v29, v40, v40
	s_nop 1
	v_permlane32_swap_b32 v43, v42
	s_nop 1
	v_permlane16_swap_b32 v45, v44
	v_add_f32_e32 v34, v35, v34
	v_add_f32_e32 v26, v27, v26
	v_add_f32_e32 v28, v28, v29
	v_mul_f32_e32 v29, v31, v31
	v_add_f32_e32 v44, v45, v44
	v_add_f32_e32 v26, v34, v26
	v_fmac_f32_e32 v29, v30, v30
	v_mul_f32_e32 v30, v33, v33
	v_mov_b32_e32 v45, v44
	v_mov_b32_e32 v27, v26
	v_fmac_f32_e32 v30, v32, v32
	v_mul_f32_e32 v11, v11, v11
	s_nop 1
	v_permlane32_swap_b32 v45, v44
	s_nop 1
	v_permlane16_swap_b32 v27, v26
	v_add_f32_e32 v29, v29, v30
	v_mul_f32_e32 v19, v19, v19
	v_fmac_f32_e32 v11, v10, v10
	v_mul_f32_e32 v10, v13, v13
	v_add_f32_e32 v26, v27, v26
	v_add_f32_e32 v28, v28, v29
	v_fmac_f32_e32 v19, v18, v18
	v_mul_f32_e32 v18, v21, v21
	v_fmac_f32_e32 v10, v12, v12
	v_mul_f32_e32 v12, v23, v23
	v_mul_f32_e32 v13, v25, v25
	v_mov_b32_e32 v27, v26
	v_mov_b32_e32 v29, v28
	v_fmac_f32_e32 v18, v20, v20
	v_fmac_f32_e32 v12, v22, v22
	v_fmac_f32_e32 v13, v24, v24
	s_nop 1
	v_permlane32_swap_b32 v27, v26
	s_nop 1
	v_permlane16_swap_b32 v29, v28
	v_add_f32_e32 v18, v19, v18
	v_add_f32_e32 v10, v11, v10
	v_add_f32_e32 v12, v12, v13
	v_mul_f32_e32 v13, v15, v15
	v_add_f32_e32 v28, v29, v28
	v_add_f32_e32 v10, v18, v10
	v_fmac_f32_e32 v13, v14, v14
	v_mul_f32_e32 v14, v17, v17
	v_mov_b32_e32 v29, v28
	v_mov_b32_e32 v11, v10
	v_fmac_f32_e32 v14, v16, v16
	s_nop 1
	v_permlane32_swap_b32 v29, v28
	s_nop 1
	v_permlane16_swap_b32 v11, v10
	v_add_f32_e32 v13, v13, v14
	v_mul_f32_e32 v7, v7, v7
	v_mul_f32_e32 v3, v3, v3
	v_add_f32_e32 v10, v11, v10
	v_add_f32_e32 v12, v12, v13
	v_fmac_f32_e32 v7, v6, v6
	v_mul_f32_e32 v6, v9, v9
	v_fmac_f32_e32 v3, v2, v2
	v_mul_f32_e32 v2, v5, v5
	v_mov_b32_e32 v11, v10
	v_mov_b32_e32 v13, v12
	v_fmac_f32_e32 v6, v8, v8
	v_fmac_f32_e32 v2, v4, v4
	s_nop 1
	v_permlane32_swap_b32 v11, v10
	s_nop 1
	v_permlane16_swap_b32 v13, v12
	v_add_f32_e32 v6, v7, v6
	v_add_f32_e32 v2, v3, v2
	v_add_f32_e32 v12, v13, v12
	v_add_f32_e32 v2, v6, v2
	v_mov_b32_e32 v13, v12
	v_mov_b32_e32 v3, v2
	s_nop 1
	v_permlane32_swap_b32 v13, v12
	s_nop 1
	v_permlane16_swap_b32 v3, v2
	s_nop 0
	v_add_f32_e32 v2, v3, v2
	v_mov_b32_e32 v3, v2
	s_nop 1
	v_permlane32_swap_b32 v3, v2
	s_and_saveexec_b64 s[46:47], s[0:1]
	s_cbranch_execz .LBB0_168
	s_lshl_b32 s2, s2, 2
	s_or_b32 s2, s2, s56
	s_ashr_i32 s3, s2, 31
	s_lshl_b64 s[48:49], s[2:3], 17
	s_add_u32 s48, s33, s48
	s_addc_u32 s49, s40, s49
	s_or_b32 s2, s2, 2
	s_ashr_i32 s3, s2, 31
	s_lshl_b64 s[2:3], s[2:3], 17
	v_add_f32_e32 v6, v3, v2
	v_lshlrev_b64 v[2:3], 2, v[142:143]
	s_add_u32 s2, s33, s2
	v_add_f32_e32 v21, v123, v122
	v_lshl_add_u64 v[4:5], s[48:49], 0, v[2:3]
	s_addc_u32 s3, s40, s3
	v_add_f32_e32 v20, v107, v106
	global_atomic_add_f32 v[4:5], v21, off
	v_lshl_add_u64 v[2:3], s[2:3], 0, v[2:3]
	v_add_f32_e32 v7, v13, v12
	v_add_f32_e32 v8, v11, v10
	v_add_f32_e32 v9, v29, v28
	v_add_f32_e32 v10, v27, v26
	v_add_f32_e32 v11, v45, v44
	v_add_f32_e32 v12, v43, v42
	v_add_f32_e32 v13, v59, v58
	v_add_f32_e32 v14, v67, v66
	v_add_f32_e32 v15, v77, v76
	v_add_f32_e32 v16, v75, v74
	v_add_f32_e32 v17, v93, v92
	v_add_f32_e32 v18, v91, v90
	v_add_f32_e32 v19, v109, v108
	global_atomic_add_f32 v[2:3], v20, off
	global_atomic_add_f32 v[4:5], v19, off offset:64
	global_atomic_add_f32 v[2:3], v18, off offset:64
	global_atomic_add_f32 v[4:5], v17, off offset:128
	global_atomic_add_f32 v[2:3], v16, off offset:128
	global_atomic_add_f32 v[4:5], v15, off offset:192
	global_atomic_add_f32 v[2:3], v14, off offset:192
	global_atomic_add_f32 v[4:5], v13, off offset:512
	global_atomic_add_f32 v[2:3], v12, off offset:512
	global_atomic_add_f32 v[4:5], v11, off offset:576
	global_atomic_add_f32 v[2:3], v10, off offset:576
	global_atomic_add_f32 v[4:5], v9, off offset:640
	global_atomic_add_f32 v[2:3], v8, off offset:640
	global_atomic_add_f32 v[4:5], v7, off offset:704
	global_atomic_add_f32 v[2:3], v6, off offset:704

; __global__ void __launch_bounds__(NWAVES * 64, 2) fwd(Args a) {
	.amdhsa_kernel _Z3fwd4Args
		.amdhsa_group_segment_fixed_size 0
		.amdhsa_private_segment_fixed_size 0
		.amdhsa_kernarg_size 440
		.amdhsa_user_sgpr_count 2
		.amdhsa_user_sgpr_dispatch_ptr 0
		.amdhsa_user_sgpr_queue_ptr 0
		.amdhsa_user_sgpr_kernarg_segment_ptr 1
		.amdhsa_user_sgpr_dispatch_id 0
		.amdhsa_user_sgpr_kernarg_preload_length 0
		.amdhsa_user_sgpr_kernarg_preload_offset 0
		.amdhsa_user_sgpr_private_segment_size 0
		.amdhsa_uses_dynamic_stack 0
		.amdhsa_enable_private_segment 0
		.amdhsa_system_sgpr_workgroup_id_x 1
		.amdhsa_system_sgpr_workgroup_id_y 0
		.amdhsa_system_sgpr_workgroup_id_z 0
		.amdhsa_system_sgpr_workgroup_info 0
		.amdhsa_system_vgpr_workitem_id 0
		.amdhsa_next_free_vgpr 251
		.amdhsa_next_free_sgpr 102
		.amdhsa_accum_offset 252
		.amdhsa_reserve_vcc 1
		.amdhsa_float_round_mode_32 0
		.amdhsa_float_round_mode_16_64 0
		.amdhsa_float_denorm_mode_32 3
		.amdhsa_float_denorm_mode_16_64 3
		.amdhsa_dx10_clamp 1
		.amdhsa_ieee_mode 1
		.amdhsa_fp16_overflow 0
		.amdhsa_tg_split 0
		.amdhsa_exception_fp_ieee_invalid_op 0
		.amdhsa_exception_fp_denorm_src 0
		.amdhsa_exception_fp_ieee_div_zero 0
		.amdhsa_exception_fp_ieee_overflow 0
		.amdhsa_exception_fp_ieee_underflow 0
		.amdhsa_exception_fp_ieee_inexact 0
		.amdhsa_exception_int_div_zero 0
	.end_amdhsa_kernel

; __global__ void __launch_bounds__(NWAVES * 64, 2) fwd(Args a) {
amdhsa.kernels:
  - .agpr_count:     0
    .args:
      - .offset:         0
        .size:           184
        .value_kind:     by_value
      - .offset:         184
        .size:           4
        .value_kind:     hidden_block_count_x
      - .offset:         188
        .size:           4
        .value_kind:     hidden_block_count_y
      - .offset:         192
        .size:           4
        .value_kind:     hidden_block_count_z
      - .offset:         196
        .size:           2
        .value_kind:     hidden_group_size_x
      - .offset:         198
        .size:           2
        .value_kind:     hidden_group_size_y
      - .offset:         200
        .size:           2
        .value_kind:     hidden_group_size_z
      - .offset:         202
        .size:           2
        .value_kind:     hidden_remainder_x
      - .offset:         204
        .size:           2
        .value_kind:     hidden_remainder_y
      - .offset:         206
        .size:           2
        .value_kind:     hidden_remainder_z
      - .offset:         224
        .size:           8
        .value_kind:     hidden_global_offset_x
      - .offset:         232
        .size:           8
        .value_kind:     hidden_global_offset_y
      - .offset:         240
        .size:           8
        .value_kind:     hidden_global_offset_z
      - .offset:         248
        .size:           2
        .value_kind:     hidden_grid_dims
      - .offset:         304
        .size:           4
        .value_kind:     hidden_dynamic_lds_size
    .group_segment_fixed_size: 0
    .kernarg_segment_align: 8
    .kernarg_segment_size: 440
    .language:       OpenCL C
    .language_version:
      - 2
      - 0
    .max_flat_workgroup_size: 512
    .name:           _Z3fwd4Args
    .private_segment_fixed_size: 0
    .sgpr_count:     108
    .sgpr_spill_count: 58
    .symbol:         _Z3fwd4Args.kd
    .uniform_work_group_size: 1
    .uses_dynamic_stack: false
    .vgpr_count:     251
    .vgpr_spill_count: 0
    .wavefront_size: 64
